# hyena epilogue 1: row and parameter loads requested before the accumulator exchange so their latency overlaps it
# speedup vs baseline: 1.0102x; 1.0051x over previous
; DI float bflo(unsigned v) { return __uint_as_float(v << 16); }
; DI float bfhi(unsigned v) { return __uint_as_float(v & 0xffff0000u); }
; DI float siluf(float x) { return x * __builtin_amdgcn_rcpf(1.f + __expf(-x)); }
; DI void hyena_item(const P& p, int l, int c, char* smem) {
;     ...
;   if (cwv) hy_conv(acc, abase, U, Zrow, a0, li, g);
;   if (cwv) {
;     const float d1 = p.fbias[(size_t)(l * 2 + 1) * 512 + c];
;     const float x0 = cw[1024 + c], x1 = cw[1536 + 1024 + c], x2 = cw[3072 + 1024 + c], xb = cbias[1024 + c];
;     const u16* rowx = p.hyT + (size_t)(1024 + c) * HYP + bt * SEQ;
;     const u16* rowg = p.hyT + (size_t)(1536 + c) * HYP + bt * SEQ;
;     u16* dst = p.YhT + (size_t)c * HYP + bt * SEQ;
; #pragma unroll
;     for (int I = 0; I < 4; ++I)
; #pragma unroll
;       for (int rq = 0; rq < 4; ++rq) {
;         const int bq = 32 * I + 8 * rq + 4 * g;
;         const int t4 = 128 * a + bq;
;         float px[4];
;         sconv4(rowx, t4, x0, x1, x2, xb, px);
;         const uint2 zv = *(const uint2*)(U + (bt * 64 + a) * 136 + bq);
;         const uint2 gv = *(const uint2*)(rowg + t4);
;         const float z1[4] = {bflo(zv.x), bfhi(zv.x), bflo(zv.y), bfhi(zv.y)};
;         const float gt[4] = {bflo(gv.x), bfhi(gv.x), bflo(gv.y), bfhi(gv.y)};
;         float yy[4];
; #pragma unroll
;         for (int j = 0; j < 4; ++j) yy[j] = px[j] * (acc[I][4 * rq + j] * invn1 + z1[j] * d1) * siluf(gt[j]);
;         uint2 ov; ov.x = pack2(yy[0], yy[1]); ov.y = pack2(yy[2], yy[3]);
;         *(uint2*)(dst + t4) = ov;
.Lhc1_done:
	v_readlane_b32 s6, v248, 24
	s_nop 1
	s_add_i32 s6, s72, s6
	s_mov_b32 s7, s57
	s_lshl_b64 s[6:7], s[6:7], 2
	s_add_u32 s6, s20, s6
	s_addc_u32 s7, s21, s7
	s_or_b32 s8, s72, 0x400
	s_mov_b32 s9, s57
	s_lshl_b64 s[14:15], s[8:9], 2
	s_add_u32 s76, s28, s14
	s_addc_u32 s77, s29, s15
	v_readlane_b32 s9, v248, 28
	s_nop 1
	s_add_u32 s14, s9, s14
	v_readlane_b32 s9, v248, 29
	s_nop 1
	s_addc_u32 s15, s9, s15
	v_and_b32_e32 v249, 0xff, v198
	v_lshlrev_b32_e32 v249, 4, v249
	v_cmp_lt_i32_e32 vcc, 0, v250
	s_cbranch_vccz .Lhy1_eh
	global_load_dword v82, v204, s[74:75] offset:2048
	global_load_dword v80, v207, s[74:75]
	global_load_dword v68, v189, s[6:7] offset:2048
	global_load_dword v83, v189, s[76:77]
	global_load_dword v70, v189, s[14:15]
	s_or_b32 s98, s72, 0x400
	s_mul_hi_u32 s99, s98, 0x8080
	s_mul_i32 s98, s98, 0x8080
	s_add_u32 s98, s36, s98
	s_addc_u32 s99, s37, s99
	s_add_u32 s98, s98, -4
	s_addc_u32 s99, s99, -1
	s_or_b32 s100, s72, 0x600
	s_mul_hi_u32 s101, s100, 0x8080
	s_mul_i32 s100, s100, 0x8080
	s_add_u32 s100, s36, s100
	s_addc_u32 s101, s37, s101
	s_add_u32 s6, s48, s96
	s_addc_u32 s7, s49, s73
	v_lshl_add_u32 v234, v233, 1, v184
	global_load_dwordx4 v[88:91], v234, s[98:99] offset:0
	global_load_dwordx2 v[92:93], v234, s[100:101] offset:0
	global_load_dwordx4 v[94:97], v234, s[98:99] offset:16
	global_load_dwordx2 v[98:99], v234, s[100:101] offset:16
	global_load_dwordx4 v[100:103], v234, s[98:99] offset:32
	global_load_dwordx2 v[104:105], v234, s[100:101] offset:32
	global_load_dwordx4 v[106:109], v234, s[98:99] offset:48
	global_load_dwordx2 v[110:111], v234, s[100:101] offset:48
	global_load_dwordx4 v[112:115], v234, s[98:99] offset:64
	global_load_dwordx2 v[116:117], v234, s[100:101] offset:64
	global_load_dwordx4 v[118:121], v234, s[98:99] offset:80
	global_load_dwordx2 v[122:123], v234, s[100:101] offset:80
	global_load_dwordx4 v[124:127], v234, s[98:99] offset:96
	global_load_dwordx2 v[128:129], v234, s[100:101] offset:96
	global_load_dwordx4 v[130:133], v234, s[98:99] offset:112
	global_load_dwordx2 v[134:135], v234, s[100:101] offset:112
	s_waitcnt lgkmcnt(0)
	s_barrier
	s_nop 7
	ds_write_b128 v249, v[16:19] offset:0
	ds_write_b128 v249, v[20:23] offset:4096
	ds_write_b128 v249, v[24:27] offset:8192
	ds_write_b128 v249, v[28:31] offset:12288
	ds_write_b128 v249, v[0:3] offset:16384
	ds_write_b128 v249, v[4:7] offset:20480
	ds_write_b128 v249, v[8:11] offset:24576
	ds_write_b128 v249, v[12:15] offset:28672
	s_waitcnt lgkmcnt(0)
	s_barrier
	ds_read_b128 v[72:75], v249 offset:32768
	ds_read_b128 v[76:79], v249 offset:36864
	ds_read_b128 v[136:139], v249 offset:40960
	ds_read_b128 v[140:143], v249 offset:45056
	ds_read_b128 v[144:147], v249 offset:49152
	ds_read_b128 v[148:151], v249 offset:53248
	ds_read_b128 v[152:155], v249 offset:57344
	ds_read_b128 v[156:159], v249 offset:61440
	s_waitcnt lgkmcnt(7)
	v_add_f32_e32 v48, v48, v72
	v_add_f32_e32 v49, v49, v73
	v_add_f32_e32 v50, v50, v74
	v_add_f32_e32 v51, v51, v75
	s_waitcnt lgkmcnt(6)
	v_add_f32_e32 v52, v52, v76
	v_add_f32_e32 v53, v53, v77
	v_add_f32_e32 v54, v54, v78
	v_add_f32_e32 v55, v55, v79
	s_waitcnt lgkmcnt(5)
	v_add_f32_e32 v56, v56, v136
	v_add_f32_e32 v57, v57, v137
	v_add_f32_e32 v58, v58, v138
	v_add_f32_e32 v59, v59, v139
	s_waitcnt lgkmcnt(4)
	v_add_f32_e32 v60, v60, v140
	v_add_f32_e32 v61, v61, v141
	v_add_f32_e32 v62, v62, v142
	v_add_f32_e32 v63, v63, v143
	s_waitcnt lgkmcnt(3)
	v_add_f32_e32 v32, v32, v144
	v_add_f32_e32 v33, v33, v145
	v_add_f32_e32 v34, v34, v146
	v_add_f32_e32 v35, v35, v147
	s_waitcnt lgkmcnt(2)
	v_add_f32_e32 v36, v36, v148
	v_add_f32_e32 v37, v37, v149
	v_add_f32_e32 v38, v38, v150
	v_add_f32_e32 v39, v39, v151
	s_waitcnt lgkmcnt(1)
	v_add_f32_e32 v40, v40, v152
	v_add_f32_e32 v41, v41, v153
	v_add_f32_e32 v42, v42, v154
	v_add_f32_e32 v43, v43, v155
	s_waitcnt lgkmcnt(0)
	v_add_f32_e32 v44, v44, v156
	v_add_f32_e32 v45, v45, v157
	v_add_f32_e32 v46, v46, v158
	v_add_f32_e32 v47, v47, v159
	v_add_f32_e32 v238, v64, v65
	v_add_f32_e32 v238, v238, v66
	v_add_f32_e32 v238, v238, v67
	v_div_scale_f32 v169, s[8:9], v238, v238, 1.0
	v_rcp_f32_e32 v170, v169
	s_nop 0
	v_fma_f32 v171, -v169, v170, 1.0
	v_fmac_f32_e32 v170, v171, v170
	v_div_scale_f32 v171, vcc, 1.0, v238, 1.0
	v_mul_f32_e32 v236, v171, v170
	v_fma_f32 v237, -v169, v236, v171
	v_fmac_f32_e32 v236, v237, v170
	v_fma_f32 v169, -v169, v236, v171
	v_div_fmas_f32 v169, v169, v170, v236
	v_div_fixup_f32 v238, v169, v238, 1.0
	v_lshl_or_b32 v235, v230, 6, v231
	v_mul_u32_u24_e32 v235, 0x110, v235
	v_lshlrev_b32_e32 v236, 1, v186
	v_add3_u32 v235, s69, v235, v236
	s_waitcnt vmcnt(8)
	ds_read_b64 v[160:161], v235 offset:0
	ds_read_b64 v[162:163], v235 offset:16
	ds_read_b64 v[164:165], v235 offset:32
	ds_read_b64 v[166:167], v235 offset:48
	v_cmp_ne_u32_e32 vcc, 0, v233
	s_nop 1
	v_and_b32_e32 v168, 0xffff0000, v88
	v_cndmask_b32_e32 v168, 0, v168, vcc
	v_lshlrev_b32_e32 v169, 16, v89
	v_and_b32_e32 v170, 0xffff0000, v89
	v_lshlrev_b32_e32 v171, 16, v90
	v_and_b32_e32 v172, 0xffff0000, v90
	v_lshlrev_b32_e32 v173, 16, v91
	v_mul_f32_e32 v178, v83, v168
	v_fmac_f32_e32 v178, v82, v169
	v_fmac_f32_e32 v178, v80, v170
	v_add_f32_e32 v178, v70, v178
	v_mul_f32_e32 v179, v83, v169
	v_fmac_f32_e32 v179, v82, v170
	v_fmac_f32_e32 v179, v80, v171
	v_add_f32_e32 v179, v70, v179
	v_mul_f32_e32 v180, v83, v170
	v_fmac_f32_e32 v180, v82, v171
	v_fmac_f32_e32 v180, v80, v172
	v_add_f32_e32 v180, v70, v180
	v_mul_f32_e32 v181, v83, v171
	v_fmac_f32_e32 v181, v82, v172
	v_fmac_f32_e32 v181, v80, v173
	v_add_f32_e32 v181, v70, v181
	s_waitcnt lgkmcnt(0)
; DI float bflo(unsigned v) { return __uint_as_float(v << 16); }
; DI float bfhi(unsigned v) { return __uint_as_float(v & 0xffff0000u); }
; DI float siluf(float x) { return x * __builtin_amdgcn_rcpf(1.f + __expf(-x)); }
; DI void hyena_item(const P& p, int l, int c, char* smem) {
;     ...
;       for (int rq = 0; rq < 4; ++rq) {
;         const int bq = 32 * I + 8 * rq + 4 * g;
;         const int t4 = 128 * a + bq;
;         float px[4];
;         sconv4(rowx, t4, x0, x1, x2, xb, px);
;         const uint2 zv = *(const uint2*)(U + (bt * 64 + a) * 136 + bq);
;         const uint2 gv = *(const uint2*)(rowg + t4);
;         const float z1[4] = {bflo(zv.x), bfhi(zv.x), bflo(zv.y), bfhi(zv.y)};
;         const float gt[4] = {bflo(gv.x), bfhi(gv.x), bflo(gv.y), bfhi(gv.y)};
;         float yy[4];
; #pragma unroll
;         for (int j = 0; j < 4; ++j) yy[j] = px[j] * (acc[I][4 * rq + j] * invn1 + z1[j] * d1) * siluf(gt[j]);
;         uint2 ov; ov.x = pack2(yy[0], yy[1]); ov.y = pack2(yy[2], yy[3]);
;         *(uint2*)(dst + t4) = ov;
	v_lshlrev_b32_e32 v174, 16, v160
	v_and_b32_e32 v175, 0xffff0000, v160
	v_lshlrev_b32_e32 v176, 16, v161
	v_and_b32_e32 v177, 0xffff0000, v161
	v_mul_f32_e32 v174, v68, v174
	v_mul_f32_e32 v175, v68, v175
	v_mul_f32_e32 v176, v68, v176
	v_mul_f32_e32 v177, v68, v177
	v_fmac_f32_e32 v174, v238, v48
	v_fmac_f32_e32 v175, v238, v49
	v_fmac_f32_e32 v176, v238, v50
	v_fmac_f32_e32 v177, v238, v51
	v_mul_f32_e32 v174, v178, v174
	v_mul_f32_e32 v175, v179, v175
	v_mul_f32_e32 v176, v180, v176
	v_mul_f32_e32 v177, v181, v177
	v_lshlrev_b32_e32 v168, 16, v92
	v_and_b32_e32 v169, 0xffff0000, v92
	v_lshlrev_b32_e32 v170, 16, v93
	v_and_b32_e32 v171, 0xffff0000, v93
	v_mul_f32_e32 v178, 0xbfb8aa3b, v168
	v_mul_f32_e32 v179, 0xbfb8aa3b, v169
	v_mul_f32_e32 v180, 0xbfb8aa3b, v170
	v_mul_f32_e32 v181, 0xbfb8aa3b, v171
	v_exp_f32_e32 v178, v178
	v_exp_f32_e32 v179, v179
	v_exp_f32_e32 v180, v180
	v_exp_f32_e32 v181, v181
	v_add_f32_e32 v178, 1.0, v178
	v_add_f32_e32 v179, 1.0, v179
	v_add_f32_e32 v180, 1.0, v180
	v_add_f32_e32 v181, 1.0, v181
	v_rcp_f32_e32 v178, v178
	v_rcp_f32_e32 v179, v179
	v_rcp_f32_e32 v180, v180
	v_rcp_f32_e32 v181, v181
	v_mul_f32_e32 v178, v178, v168
	v_mul_f32_e32 v179, v179, v169
	v_mul_f32_e32 v180, v180, v170
	v_mul_f32_e32 v181, v181, v171
	v_mul_f32_e32 v174, v174, v178
	v_mul_f32_e32 v175, v175, v179
	v_mul_f32_e32 v176, v176, v180
	v_mul_f32_e32 v177, v177, v181
	v_cvt_pk_bf16_f32 v182, v174, v175
	v_cvt_pk_bf16_f32 v183, v176, v177
	global_store_dwordx2 v234, v[182:183], s[6:7] offset:0
	v_and_b32_e32 v168, 0xffff0000, v94
	v_lshlrev_b32_e32 v169, 16, v95
	v_and_b32_e32 v170, 0xffff0000, v95
	v_lshlrev_b32_e32 v171, 16, v96
	v_and_b32_e32 v172, 0xffff0000, v96
	v_lshlrev_b32_e32 v173, 16, v97
	v_mul_f32_e32 v178, v83, v168
	v_fmac_f32_e32 v178, v82, v169
	v_fmac_f32_e32 v178, v80, v170
	v_add_f32_e32 v178, v70, v178
	v_mul_f32_e32 v179, v83, v169
	v_fmac_f32_e32 v179, v82, v170
	v_fmac_f32_e32 v179, v80, v171
	v_add_f32_e32 v179, v70, v179
	v_mul_f32_e32 v180, v83, v170
	v_fmac_f32_e32 v180, v82, v171
	v_fmac_f32_e32 v180, v80, v172
	v_add_f32_e32 v180, v70, v180
	v_mul_f32_e32 v181, v83, v171
	v_fmac_f32_e32 v181, v82, v172
	v_fmac_f32_e32 v181, v80, v173
	v_add_f32_e32 v181, v70, v181
	v_lshlrev_b32_e32 v174, 16, v162
	v_and_b32_e32 v175, 0xffff0000, v162
	v_lshlrev_b32_e32 v176, 16, v163
	v_and_b32_e32 v177, 0xffff0000, v163
	v_mul_f32_e32 v174, v68, v174
	v_mul_f32_e32 v175, v68, v175
	v_mul_f32_e32 v176, v68, v176
	v_mul_f32_e32 v177, v68, v177
	v_fmac_f32_e32 v174, v238, v52
	v_fmac_f32_e32 v175, v238, v53
	v_fmac_f32_e32 v176, v238, v54
	v_fmac_f32_e32 v177, v238, v55
	v_mul_f32_e32 v174, v178, v174
	v_mul_f32_e32 v175, v179, v175
	v_mul_f32_e32 v176, v180, v176
	v_mul_f32_e32 v177, v181, v177
	v_lshlrev_b32_e32 v168, 16, v98
	v_and_b32_e32 v169, 0xffff0000, v98
	v_lshlrev_b32_e32 v170, 16, v99
	v_and_b32_e32 v171, 0xffff0000, v99
	v_mul_f32_e32 v178, 0xbfb8aa3b, v168
	v_mul_f32_e32 v179, 0xbfb8aa3b, v169
	v_mul_f32_e32 v180, 0xbfb8aa3b, v170
	v_mul_f32_e32 v181, 0xbfb8aa3b, v171
	v_exp_f32_e32 v178, v178
	v_exp_f32_e32 v179, v179
	v_exp_f32_e32 v180, v180
	v_exp_f32_e32 v181, v181
	v_add_f32_e32 v178, 1.0, v178
	v_add_f32_e32 v179, 1.0, v179
	v_add_f32_e32 v180, 1.0, v180
	v_add_f32_e32 v181, 1.0, v181
	v_rcp_f32_e32 v178, v178
	v_rcp_f32_e32 v179, v179
	v_rcp_f32_e32 v180, v180
	v_rcp_f32_e32 v181, v181
	v_mul_f32_e32 v178, v178, v168
	v_mul_f32_e32 v179, v179, v169
	v_mul_f32_e32 v180, v180, v170
	v_mul_f32_e32 v181, v181, v171
	v_mul_f32_e32 v174, v174, v178
	v_mul_f32_e32 v175, v175, v179
	v_mul_f32_e32 v176, v176, v180
	v_mul_f32_e32 v177, v177, v181
	v_cvt_pk_bf16_f32 v182, v174, v175
	v_cvt_pk_bf16_f32 v183, v176, v177
	global_store_dwordx2 v234, v[182:183], s[6:7] offset:16
	v_and_b32_e32 v168, 0xffff0000, v100
	v_lshlrev_b32_e32 v169, 16, v101
	v_and_b32_e32 v170, 0xffff0000, v101
	v_lshlrev_b32_e32 v171, 16, v102
	v_and_b32_e32 v172, 0xffff0000, v102
	v_lshlrev_b32_e32 v173, 16, v103
	v_mul_f32_e32 v178, v83, v168
	v_fmac_f32_e32 v178, v82, v169
	v_fmac_f32_e32 v178, v80, v170
	v_add_f32_e32 v178, v70, v178
	v_mul_f32_e32 v179, v83, v169
	v_fmac_f32_e32 v179, v82, v170
	v_fmac_f32_e32 v179, v80, v171
	v_add_f32_e32 v179, v70, v179
	v_mul_f32_e32 v180, v83, v170
	v_fmac_f32_e32 v180, v82, v171
	v_fmac_f32_e32 v180, v80, v172
	v_add_f32_e32 v180, v70, v180
	v_mul_f32_e32 v181, v83, v171
	v_fmac_f32_e32 v181, v82, v172
	v_fmac_f32_e32 v181, v80, v173
	v_add_f32_e32 v181, v70, v181
	v_lshlrev_b32_e32 v174, 16, v164
	v_and_b32_e32 v175, 0xffff0000, v164
	v_lshlrev_b32_e32 v176, 16, v165
	v_and_b32_e32 v177, 0xffff0000, v165
	v_mul_f32_e32 v174, v68, v174
	v_mul_f32_e32 v175, v68, v175
	v_mul_f32_e32 v176, v68, v176
	v_mul_f32_e32 v177, v68, v177
	v_fmac_f32_e32 v174, v238, v56
	v_fmac_f32_e32 v175, v238, v57
	v_fmac_f32_e32 v176, v238, v58
	v_fmac_f32_e32 v177, v238, v59
	v_mul_f32_e32 v174, v178, v174
	v_mul_f32_e32 v175, v179, v175
	v_mul_f32_e32 v176, v180, v176
	v_mul_f32_e32 v177, v181, v177
	v_lshlrev_b32_e32 v168, 16, v104
	v_and_b32_e32 v169, 0xffff0000, v104
	v_lshlrev_b32_e32 v170, 16, v105
	v_and_b32_e32 v171, 0xffff0000, v105
	v_mul_f32_e32 v178, 0xbfb8aa3b, v168
	v_mul_f32_e32 v179, 0xbfb8aa3b, v169
	v_mul_f32_e32 v180, 0xbfb8aa3b, v170
	v_mul_f32_e32 v181, 0xbfb8aa3b, v171
	v_exp_f32_e32 v178, v178
	v_exp_f32_e32 v179, v179
	v_exp_f32_e32 v180, v180
	v_exp_f32_e32 v181, v181
	v_add_f32_e32 v178, 1.0, v178
	v_add_f32_e32 v179, 1.0, v179
	v_add_f32_e32 v180, 1.0, v180
	v_add_f32_e32 v181, 1.0, v181
	v_rcp_f32_e32 v178, v178
	v_rcp_f32_e32 v179, v179
	v_rcp_f32_e32 v180, v180
	v_rcp_f32_e32 v181, v181
; DI float bflo(unsigned v) { return __uint_as_float(v << 16); }
; DI float bfhi(unsigned v) { return __uint_as_float(v & 0xffff0000u); }
; DI float siluf(float x) { return x * __builtin_amdgcn_rcpf(1.f + __expf(-x)); }
; DI void hyena_item(const P& p, int l, int c, char* smem) {
;     ...
;       for (int rq = 0; rq < 4; ++rq) {
;         const int bq = 32 * I + 8 * rq + 4 * g;
;         const int t4 = 128 * a + bq;
;         float px[4];
;         sconv4(rowx, t4, x0, x1, x2, xb, px);
;         const uint2 zv = *(const uint2*)(U + (bt * 64 + a) * 136 + bq);
;         const uint2 gv = *(const uint2*)(rowg + t4);
;         const float z1[4] = {bflo(zv.x), bfhi(zv.x), bflo(zv.y), bfhi(zv.y)};
;         const float gt[4] = {bflo(gv.x), bfhi(gv.x), bflo(gv.y), bfhi(gv.y)};
;         float yy[4];
; #pragma unroll
;         for (int j = 0; j < 4; ++j) yy[j] = px[j] * (acc[I][4 * rq + j] * invn1 + z1[j] * d1) * siluf(gt[j]);
;         uint2 ov; ov.x = pack2(yy[0], yy[1]); ov.y = pack2(yy[2], yy[3]);
;         *(uint2*)(dst + t4) = ov;
	v_mul_f32_e32 v178, v178, v168
	v_mul_f32_e32 v179, v179, v169
	v_mul_f32_e32 v180, v180, v170
	v_mul_f32_e32 v181, v181, v171
	v_mul_f32_e32 v174, v174, v178
	v_mul_f32_e32 v175, v175, v179
	v_mul_f32_e32 v176, v176, v180
	v_mul_f32_e32 v177, v177, v181
	v_cvt_pk_bf16_f32 v182, v174, v175
	v_cvt_pk_bf16_f32 v183, v176, v177
	global_store_dwordx2 v234, v[182:183], s[6:7] offset:32
	v_and_b32_e32 v168, 0xffff0000, v106
	v_lshlrev_b32_e32 v169, 16, v107
	v_and_b32_e32 v170, 0xffff0000, v107
	v_lshlrev_b32_e32 v171, 16, v108
	v_and_b32_e32 v172, 0xffff0000, v108
	v_lshlrev_b32_e32 v173, 16, v109
	v_mul_f32_e32 v178, v83, v168
	v_fmac_f32_e32 v178, v82, v169
	v_fmac_f32_e32 v178, v80, v170
	v_add_f32_e32 v178, v70, v178
	v_mul_f32_e32 v179, v83, v169
	v_fmac_f32_e32 v179, v82, v170
	v_fmac_f32_e32 v179, v80, v171
	v_add_f32_e32 v179, v70, v179
	v_mul_f32_e32 v180, v83, v170
	v_fmac_f32_e32 v180, v82, v171
	v_fmac_f32_e32 v180, v80, v172
	v_add_f32_e32 v180, v70, v180
	v_mul_f32_e32 v181, v83, v171
	v_fmac_f32_e32 v181, v82, v172
	v_fmac_f32_e32 v181, v80, v173
	v_add_f32_e32 v181, v70, v181
	v_lshlrev_b32_e32 v174, 16, v166
	v_and_b32_e32 v175, 0xffff0000, v166
	v_lshlrev_b32_e32 v176, 16, v167
	v_and_b32_e32 v177, 0xffff0000, v167
	v_mul_f32_e32 v174, v68, v174
	v_mul_f32_e32 v175, v68, v175
	v_mul_f32_e32 v176, v68, v176
	v_mul_f32_e32 v177, v68, v177
	v_fmac_f32_e32 v174, v238, v60
	v_fmac_f32_e32 v175, v238, v61
	v_fmac_f32_e32 v176, v238, v62
	v_fmac_f32_e32 v177, v238, v63
	v_mul_f32_e32 v174, v178, v174
	v_mul_f32_e32 v175, v179, v175
	v_mul_f32_e32 v176, v180, v176
	v_mul_f32_e32 v177, v181, v177
	v_lshlrev_b32_e32 v168, 16, v110
	v_and_b32_e32 v169, 0xffff0000, v110
	v_lshlrev_b32_e32 v170, 16, v111
	v_and_b32_e32 v171, 0xffff0000, v111
	v_mul_f32_e32 v178, 0xbfb8aa3b, v168
	v_mul_f32_e32 v179, 0xbfb8aa3b, v169
	v_mul_f32_e32 v180, 0xbfb8aa3b, v170
	v_mul_f32_e32 v181, 0xbfb8aa3b, v171
	v_exp_f32_e32 v178, v178
	v_exp_f32_e32 v179, v179
	v_exp_f32_e32 v180, v180
	v_exp_f32_e32 v181, v181
	v_add_f32_e32 v178, 1.0, v178
	v_add_f32_e32 v179, 1.0, v179
	v_add_f32_e32 v180, 1.0, v180
	v_add_f32_e32 v181, 1.0, v181
	v_rcp_f32_e32 v178, v178
	v_rcp_f32_e32 v179, v179
	v_rcp_f32_e32 v180, v180
	v_rcp_f32_e32 v181, v181
	v_mul_f32_e32 v178, v178, v168
	v_mul_f32_e32 v179, v179, v169
	v_mul_f32_e32 v180, v180, v170
	v_mul_f32_e32 v181, v181, v171
	v_mul_f32_e32 v174, v174, v178
	v_mul_f32_e32 v175, v175, v179
	v_mul_f32_e32 v176, v176, v180
	v_mul_f32_e32 v177, v177, v181
	v_cvt_pk_bf16_f32 v182, v174, v175
	v_cvt_pk_bf16_f32 v183, v176, v177
	global_store_dwordx2 v234, v[182:183], s[6:7] offset:48
	s_waitcnt vmcnt(4)
	ds_read_b64 v[160:161], v235 offset:64
	ds_read_b64 v[162:163], v235 offset:80
	ds_read_b64 v[164:165], v235 offset:96
	ds_read_b64 v[166:167], v235 offset:112
	v_and_b32_e32 v168, 0xffff0000, v112
	v_lshlrev_b32_e32 v169, 16, v113
	v_and_b32_e32 v170, 0xffff0000, v113
	v_lshlrev_b32_e32 v171, 16, v114
	v_and_b32_e32 v172, 0xffff0000, v114
	v_lshlrev_b32_e32 v173, 16, v115
	v_mul_f32_e32 v178, v83, v168
	v_fmac_f32_e32 v178, v82, v169
	v_fmac_f32_e32 v178, v80, v170
	v_add_f32_e32 v178, v70, v178
	v_mul_f32_e32 v179, v83, v169
	v_fmac_f32_e32 v179, v82, v170
	v_fmac_f32_e32 v179, v80, v171
	v_add_f32_e32 v179, v70, v179
	v_mul_f32_e32 v180, v83, v170
	v_fmac_f32_e32 v180, v82, v171
	v_fmac_f32_e32 v180, v80, v172
	v_add_f32_e32 v180, v70, v180
	v_mul_f32_e32 v181, v83, v171
	v_fmac_f32_e32 v181, v82, v172
	v_fmac_f32_e32 v181, v80, v173
	v_add_f32_e32 v181, v70, v181
	s_waitcnt lgkmcnt(0)
	v_lshlrev_b32_e32 v174, 16, v160
	v_and_b32_e32 v175, 0xffff0000, v160
	v_lshlrev_b32_e32 v176, 16, v161
	v_and_b32_e32 v177, 0xffff0000, v161
	v_mul_f32_e32 v174, v68, v174
	v_mul_f32_e32 v175, v68, v175
	v_mul_f32_e32 v176, v68, v176
	v_mul_f32_e32 v177, v68, v177
	v_fmac_f32_e32 v174, v238, v32
	v_fmac_f32_e32 v175, v238, v33
	v_fmac_f32_e32 v176, v238, v34
	v_fmac_f32_e32 v177, v238, v35
	v_mul_f32_e32 v174, v178, v174
	v_mul_f32_e32 v175, v179, v175
	v_mul_f32_e32 v176, v180, v176
	v_mul_f32_e32 v177, v181, v177
	v_lshlrev_b32_e32 v168, 16, v116
	v_and_b32_e32 v169, 0xffff0000, v116
	v_lshlrev_b32_e32 v170, 16, v117
	v_and_b32_e32 v171, 0xffff0000, v117
	v_mul_f32_e32 v178, 0xbfb8aa3b, v168
	v_mul_f32_e32 v179, 0xbfb8aa3b, v169
	v_mul_f32_e32 v180, 0xbfb8aa3b, v170
	v_mul_f32_e32 v181, 0xbfb8aa3b, v171
	v_exp_f32_e32 v178, v178
	v_exp_f32_e32 v179, v179
	v_exp_f32_e32 v180, v180
	v_exp_f32_e32 v181, v181
	v_add_f32_e32 v178, 1.0, v178
	v_add_f32_e32 v179, 1.0, v179
	v_add_f32_e32 v180, 1.0, v180
	v_add_f32_e32 v181, 1.0, v181
	v_rcp_f32_e32 v178, v178
	v_rcp_f32_e32 v179, v179
	v_rcp_f32_e32 v180, v180
	v_rcp_f32_e32 v181, v181
	v_mul_f32_e32 v178, v178, v168
	v_mul_f32_e32 v179, v179, v169
	v_mul_f32_e32 v180, v180, v170
	v_mul_f32_e32 v181, v181, v171
	v_mul_f32_e32 v174, v174, v178
	v_mul_f32_e32 v175, v175, v179
	v_mul_f32_e32 v176, v176, v180
	v_mul_f32_e32 v177, v177, v181
	v_cvt_pk_bf16_f32 v182, v174, v175
	v_cvt_pk_bf16_f32 v183, v176, v177
	global_store_dwordx2 v234, v[182:183], s[6:7] offset:64
	v_and_b32_e32 v168, 0xffff0000, v118
	v_lshlrev_b32_e32 v169, 16, v119
	v_and_b32_e32 v170, 0xffff0000, v119
	v_lshlrev_b32_e32 v171, 16, v120
	v_and_b32_e32 v172, 0xffff0000, v120
	v_lshlrev_b32_e32 v173, 16, v121
	v_mul_f32_e32 v178, v83, v168
	v_fmac_f32_e32 v178, v82, v169
	v_fmac_f32_e32 v178, v80, v170
	v_add_f32_e32 v178, v70, v178
	v_mul_f32_e32 v179, v83, v169
	v_fmac_f32_e32 v179, v82, v170
	v_fmac_f32_e32 v179, v80, v171
	v_add_f32_e32 v179, v70, v179
	v_mul_f32_e32 v180, v83, v170
	v_fmac_f32_e32 v180, v82, v171
; DI float bflo(unsigned v) { return __uint_as_float(v << 16); }
; DI float bfhi(unsigned v) { return __uint_as_float(v & 0xffff0000u); }
; DI float siluf(float x) { return x * __builtin_amdgcn_rcpf(1.f + __expf(-x)); }
; DI void hyena_item(const P& p, int l, int c, char* smem) {
;     ...
;       for (int rq = 0; rq < 4; ++rq) {
;         const int bq = 32 * I + 8 * rq + 4 * g;
;         const int t4 = 128 * a + bq;
;         float px[4];
;         sconv4(rowx, t4, x0, x1, x2, xb, px);
;         const uint2 zv = *(const uint2*)(U + (bt * 64 + a) * 136 + bq);
;         const uint2 gv = *(const uint2*)(rowg + t4);
;         const float z1[4] = {bflo(zv.x), bfhi(zv.x), bflo(zv.y), bfhi(zv.y)};
;         const float gt[4] = {bflo(gv.x), bfhi(gv.x), bflo(gv.y), bfhi(gv.y)};
;         float yy[4];
; #pragma unroll
;         for (int j = 0; j < 4; ++j) yy[j] = px[j] * (acc[I][4 * rq + j] * invn1 + z1[j] * d1) * siluf(gt[j]);
;         uint2 ov; ov.x = pack2(yy[0], yy[1]); ov.y = pack2(yy[2], yy[3]);
;         *(uint2*)(dst + t4) = ov;
	v_fmac_f32_e32 v180, v80, v172
	v_add_f32_e32 v180, v70, v180
	v_mul_f32_e32 v181, v83, v171
	v_fmac_f32_e32 v181, v82, v172
	v_fmac_f32_e32 v181, v80, v173
	v_add_f32_e32 v181, v70, v181
	v_lshlrev_b32_e32 v174, 16, v162
	v_and_b32_e32 v175, 0xffff0000, v162
	v_lshlrev_b32_e32 v176, 16, v163
	v_and_b32_e32 v177, 0xffff0000, v163
	v_mul_f32_e32 v174, v68, v174
	v_mul_f32_e32 v175, v68, v175
	v_mul_f32_e32 v176, v68, v176
	v_mul_f32_e32 v177, v68, v177
	v_fmac_f32_e32 v174, v238, v36
	v_fmac_f32_e32 v175, v238, v37
	v_fmac_f32_e32 v176, v238, v38
	v_fmac_f32_e32 v177, v238, v39
	v_mul_f32_e32 v174, v178, v174
	v_mul_f32_e32 v175, v179, v175
	v_mul_f32_e32 v176, v180, v176
	v_mul_f32_e32 v177, v181, v177
	v_lshlrev_b32_e32 v168, 16, v122
	v_and_b32_e32 v169, 0xffff0000, v122
	v_lshlrev_b32_e32 v170, 16, v123
	v_and_b32_e32 v171, 0xffff0000, v123
	v_mul_f32_e32 v178, 0xbfb8aa3b, v168
	v_mul_f32_e32 v179, 0xbfb8aa3b, v169
	v_mul_f32_e32 v180, 0xbfb8aa3b, v170
	v_mul_f32_e32 v181, 0xbfb8aa3b, v171
	v_exp_f32_e32 v178, v178
	v_exp_f32_e32 v179, v179
	v_exp_f32_e32 v180, v180
	v_exp_f32_e32 v181, v181
	v_add_f32_e32 v178, 1.0, v178
	v_add_f32_e32 v179, 1.0, v179
	v_add_f32_e32 v180, 1.0, v180
	v_add_f32_e32 v181, 1.0, v181
	v_rcp_f32_e32 v178, v178
	v_rcp_f32_e32 v179, v179
	v_rcp_f32_e32 v180, v180
	v_rcp_f32_e32 v181, v181
	v_mul_f32_e32 v178, v178, v168
	v_mul_f32_e32 v179, v179, v169
	v_mul_f32_e32 v180, v180, v170
	v_mul_f32_e32 v181, v181, v171
	v_mul_f32_e32 v174, v174, v178
	v_mul_f32_e32 v175, v175, v179
	v_mul_f32_e32 v176, v176, v180
	v_mul_f32_e32 v177, v177, v181
	v_cvt_pk_bf16_f32 v182, v174, v175
	v_cvt_pk_bf16_f32 v183, v176, v177
	global_store_dwordx2 v234, v[182:183], s[6:7] offset:80
	v_and_b32_e32 v168, 0xffff0000, v124
	v_lshlrev_b32_e32 v169, 16, v125
	v_and_b32_e32 v170, 0xffff0000, v125
	v_lshlrev_b32_e32 v171, 16, v126
	v_and_b32_e32 v172, 0xffff0000, v126
	v_lshlrev_b32_e32 v173, 16, v127
	v_mul_f32_e32 v178, v83, v168
	v_fmac_f32_e32 v178, v82, v169
	v_fmac_f32_e32 v178, v80, v170
	v_add_f32_e32 v178, v70, v178
	v_mul_f32_e32 v179, v83, v169
	v_fmac_f32_e32 v179, v82, v170
	v_fmac_f32_e32 v179, v80, v171
	v_add_f32_e32 v179, v70, v179
	v_mul_f32_e32 v180, v83, v170
	v_fmac_f32_e32 v180, v82, v171
	v_fmac_f32_e32 v180, v80, v172
	v_add_f32_e32 v180, v70, v180
	v_mul_f32_e32 v181, v83, v171
	v_fmac_f32_e32 v181, v82, v172
	v_fmac_f32_e32 v181, v80, v173
	v_add_f32_e32 v181, v70, v181
	v_lshlrev_b32_e32 v174, 16, v164
	v_and_b32_e32 v175, 0xffff0000, v164
	v_lshlrev_b32_e32 v176, 16, v165
	v_and_b32_e32 v177, 0xffff0000, v165
	v_mul_f32_e32 v174, v68, v174
	v_mul_f32_e32 v175, v68, v175
	v_mul_f32_e32 v176, v68, v176
	v_mul_f32_e32 v177, v68, v177
	v_fmac_f32_e32 v174, v238, v40
	v_fmac_f32_e32 v175, v238, v41
	v_fmac_f32_e32 v176, v238, v42
	v_fmac_f32_e32 v177, v238, v43
	v_mul_f32_e32 v174, v178, v174
	v_mul_f32_e32 v175, v179, v175
	v_mul_f32_e32 v176, v180, v176
	v_mul_f32_e32 v177, v181, v177
	v_lshlrev_b32_e32 v168, 16, v128
	v_and_b32_e32 v169, 0xffff0000, v128
	v_lshlrev_b32_e32 v170, 16, v129
	v_and_b32_e32 v171, 0xffff0000, v129
	v_mul_f32_e32 v178, 0xbfb8aa3b, v168
	v_mul_f32_e32 v179, 0xbfb8aa3b, v169
	v_mul_f32_e32 v180, 0xbfb8aa3b, v170
	v_mul_f32_e32 v181, 0xbfb8aa3b, v171
	v_exp_f32_e32 v178, v178
	v_exp_f32_e32 v179, v179
	v_exp_f32_e32 v180, v180
	v_exp_f32_e32 v181, v181
	v_add_f32_e32 v178, 1.0, v178
	v_add_f32_e32 v179, 1.0, v179
	v_add_f32_e32 v180, 1.0, v180
	v_add_f32_e32 v181, 1.0, v181
	v_rcp_f32_e32 v178, v178
	v_rcp_f32_e32 v179, v179
	v_rcp_f32_e32 v180, v180
	v_rcp_f32_e32 v181, v181
	v_mul_f32_e32 v178, v178, v168
	v_mul_f32_e32 v179, v179, v169
	v_mul_f32_e32 v180, v180, v170
	v_mul_f32_e32 v181, v181, v171
	v_mul_f32_e32 v174, v174, v178
	v_mul_f32_e32 v175, v175, v179
	v_mul_f32_e32 v176, v176, v180
	v_mul_f32_e32 v177, v177, v181
	v_cvt_pk_bf16_f32 v182, v174, v175
	v_cvt_pk_bf16_f32 v183, v176, v177
	global_store_dwordx2 v234, v[182:183], s[6:7] offset:96
	v_and_b32_e32 v168, 0xffff0000, v130
	v_lshlrev_b32_e32 v169, 16, v131
	v_and_b32_e32 v170, 0xffff0000, v131
	v_lshlrev_b32_e32 v171, 16, v132
	v_and_b32_e32 v172, 0xffff0000, v132
	v_lshlrev_b32_e32 v173, 16, v133
	v_mul_f32_e32 v178, v83, v168
	v_fmac_f32_e32 v178, v82, v169
	v_fmac_f32_e32 v178, v80, v170
	v_add_f32_e32 v178, v70, v178
	v_mul_f32_e32 v179, v83, v169
	v_fmac_f32_e32 v179, v82, v170
	v_fmac_f32_e32 v179, v80, v171
	v_add_f32_e32 v179, v70, v179
	v_mul_f32_e32 v180, v83, v170
	v_fmac_f32_e32 v180, v82, v171
	v_fmac_f32_e32 v180, v80, v172
	v_add_f32_e32 v180, v70, v180
	v_mul_f32_e32 v181, v83, v171
	v_fmac_f32_e32 v181, v82, v172
	v_fmac_f32_e32 v181, v80, v173
	v_add_f32_e32 v181, v70, v181
	v_lshlrev_b32_e32 v174, 16, v166
	v_and_b32_e32 v175, 0xffff0000, v166
	v_lshlrev_b32_e32 v176, 16, v167
	v_and_b32_e32 v177, 0xffff0000, v167
	v_mul_f32_e32 v174, v68, v174
	v_mul_f32_e32 v175, v68, v175
	v_mul_f32_e32 v176, v68, v176
	v_mul_f32_e32 v177, v68, v177
	v_fmac_f32_e32 v174, v238, v44
	v_fmac_f32_e32 v175, v238, v45
	v_fmac_f32_e32 v176, v238, v46
	v_fmac_f32_e32 v177, v238, v47
	v_mul_f32_e32 v174, v178, v174
	v_mul_f32_e32 v175, v179, v175
	v_mul_f32_e32 v176, v180, v176
	v_mul_f32_e32 v177, v181, v177
	v_lshlrev_b32_e32 v168, 16, v134
	v_and_b32_e32 v169, 0xffff0000, v134
	v_lshlrev_b32_e32 v170, 16, v135
	v_and_b32_e32 v171, 0xffff0000, v135
	v_mul_f32_e32 v178, 0xbfb8aa3b, v168
	v_mul_f32_e32 v179, 0xbfb8aa3b, v169
	v_mul_f32_e32 v180, 0xbfb8aa3b, v170
	v_mul_f32_e32 v181, 0xbfb8aa3b, v171
	v_exp_f32_e32 v178, v178
	v_exp_f32_e32 v179, v179
	v_exp_f32_e32 v180, v180
	v_exp_f32_e32 v181, v181
	v_add_f32_e32 v178, 1.0, v178
	v_add_f32_e32 v179, 1.0, v179
	v_add_f32_e32 v180, 1.0, v180
	v_add_f32_e32 v181, 1.0, v181
	v_rcp_f32_e32 v178, v178
	v_rcp_f32_e32 v179, v179
	v_rcp_f32_e32 v180, v180
	v_rcp_f32_e32 v181, v181
	v_mul_f32_e32 v178, v178, v168
	v_mul_f32_e32 v179, v179, v169
	v_mul_f32_e32 v180, v180, v170
	v_mul_f32_e32 v181, v181, v171
	v_mul_f32_e32 v174, v174, v178
	v_mul_f32_e32 v175, v175, v179
	v_mul_f32_e32 v176, v176, v180
	v_mul_f32_e32 v177, v177, v181
	v_cvt_pk_bf16_f32 v182, v174, v175
	v_cvt_pk_bf16_f32 v183, v176, v177
	global_store_dwordx2 v234, v[182:183], s[6:7] offset:112
	s_branch .Lhy1_skip
; DI float bflo(unsigned v) { return __uint_as_float(v << 16); }
; DI float bfhi(unsigned v) { return __uint_as_float(v & 0xffff0000u); }
; DI float siluf(float x) { return x * __builtin_amdgcn_rcpf(1.f + __expf(-x)); }
; DI void hyena_item(const P& p, int l, int c, char* smem) {
;     ...
;   const float invn0 = 1.0f / (misc[4] + misc[5] + misc[6] + misc[7]);
;   const float invn1 = 1.0f / (misc[8] + misc[9] + misc[10] + misc[11]);
;     ...
;   if (cwv) hy_conv(acc, abase, U, Zrow, a0, li, g);
;   if (cwv) {
;     const float d1 = p.fbias[(size_t)(l * 2 + 1) * 512 + c];
;     const float x0 = cw[1024 + c], x1 = cw[1536 + 1024 + c], x2 = cw[3072 + 1024 + c], xb = cbias[1024 + c];
;     const u16* rowx = p.hyT + (size_t)(1024 + c) * HYP + bt * SEQ;
;     const u16* rowg = p.hyT + (size_t)(1536 + c) * HYP + bt * SEQ;
;     u16* dst = p.YhT + (size_t)c * HYP + bt * SEQ;
; #pragma unroll
;     for (int I = 0; I < 4; ++I)
; #pragma unroll
;       for (int rq = 0; rq < 4; ++rq) {
;         const int bq = 32 * I + 8 * rq + 4 * g;
;         const int t4 = 128 * a + bq;
;         float px[4];
;         sconv4(rowx, t4, x0, x1, x2, xb, px);
;         const uint2 zv = *(const uint2*)(U + (bt * 64 + a) * 136 + bq);
;         const uint2 gv = *(const uint2*)(rowg + t4);
;         const float z1[4] = {bflo(zv.x), bfhi(zv.x), bflo(zv.y), bfhi(zv.y)};
;         const float gt[4] = {bflo(gv.x), bfhi(gv.x), bflo(gv.y), bfhi(gv.y)};
;         float yy[4];
; #pragma unroll
;         for (int j = 0; j < 4; ++j) yy[j] = px[j] * (acc[I][4 * rq + j] * invn1 + z1[j] * d1) * siluf(gt[j]);
;         uint2 ov; ov.x = pack2(yy[0], yy[1]); ov.y = pack2(yy[2], yy[3]);
;         *(uint2*)(dst + t4) = ov;
.Lhy1_eh:
	global_load_dword v82, v204, s[74:75] offset:2048
	global_load_dword v80, v207, s[74:75]
	global_load_dword v68, v189, s[6:7] offset:2048
	global_load_dword v83, v189, s[76:77]
	global_load_dword v70, v189, s[14:15]
	s_or_b32 s98, s72, 0x400
	s_mul_hi_u32 s99, s98, 0x8080
	s_mul_i32 s98, s98, 0x8080
	s_add_u32 s98, s36, s98
	s_addc_u32 s99, s37, s99
	s_add_u32 s98, s98, -4
	s_addc_u32 s99, s99, -1
	s_or_b32 s100, s72, 0x600
	s_mul_hi_u32 s101, s100, 0x8080
	s_mul_i32 s100, s100, 0x8080
	s_add_u32 s100, s36, s100
	s_addc_u32 s101, s37, s101
	s_add_u32 s6, s48, s96
	s_addc_u32 s7, s49, s73
	v_lshl_add_u32 v234, v233, 1, v184
	global_load_dwordx4 v[88:91], v234, s[98:99] offset:128
	global_load_dwordx2 v[92:93], v234, s[100:101] offset:128
	global_load_dwordx4 v[94:97], v234, s[98:99] offset:144
	global_load_dwordx2 v[98:99], v234, s[100:101] offset:144
	global_load_dwordx4 v[100:103], v234, s[98:99] offset:160
	global_load_dwordx2 v[104:105], v234, s[100:101] offset:160
	global_load_dwordx4 v[106:109], v234, s[98:99] offset:176
	global_load_dwordx2 v[110:111], v234, s[100:101] offset:176
	global_load_dwordx4 v[112:115], v234, s[98:99] offset:192
	global_load_dwordx2 v[116:117], v234, s[100:101] offset:192
	global_load_dwordx4 v[118:121], v234, s[98:99] offset:208
	global_load_dwordx2 v[122:123], v234, s[100:101] offset:208
	global_load_dwordx4 v[124:127], v234, s[98:99] offset:224
	global_load_dwordx2 v[128:129], v234, s[100:101] offset:224
	global_load_dwordx4 v[130:133], v234, s[98:99] offset:240
	global_load_dwordx2 v[134:135], v234, s[100:101] offset:240
	s_waitcnt lgkmcnt(0)
	s_barrier
	s_nop 7
	ds_write_b128 v249, v[48:51] offset:32768
	ds_write_b128 v249, v[52:55] offset:36864
	ds_write_b128 v249, v[56:59] offset:40960
	ds_write_b128 v249, v[60:63] offset:45056
	ds_write_b128 v249, v[32:35] offset:49152
	ds_write_b128 v249, v[36:39] offset:53248
	ds_write_b128 v249, v[40:43] offset:57344
	ds_write_b128 v249, v[44:47] offset:61440
	s_waitcnt lgkmcnt(0)
	s_barrier
	ds_read_b128 v[72:75], v249 offset:0
	ds_read_b128 v[76:79], v249 offset:4096
	ds_read_b128 v[136:139], v249 offset:8192
	ds_read_b128 v[140:143], v249 offset:12288
	ds_read_b128 v[144:147], v249 offset:16384
	ds_read_b128 v[148:151], v249 offset:20480
	ds_read_b128 v[152:155], v249 offset:24576
	ds_read_b128 v[156:159], v249 offset:28672
	s_waitcnt lgkmcnt(7)
	v_add_f32_e32 v16, v16, v72
	v_add_f32_e32 v17, v17, v73
	v_add_f32_e32 v18, v18, v74
	v_add_f32_e32 v19, v19, v75
	s_waitcnt lgkmcnt(6)
	v_add_f32_e32 v20, v20, v76
	v_add_f32_e32 v21, v21, v77
	v_add_f32_e32 v22, v22, v78
	v_add_f32_e32 v23, v23, v79
	s_waitcnt lgkmcnt(5)
	v_add_f32_e32 v24, v24, v136
	v_add_f32_e32 v25, v25, v137
	v_add_f32_e32 v26, v26, v138
	v_add_f32_e32 v27, v27, v139
	s_waitcnt lgkmcnt(4)
	v_add_f32_e32 v28, v28, v140
	v_add_f32_e32 v29, v29, v141
	v_add_f32_e32 v30, v30, v142
	v_add_f32_e32 v31, v31, v143
	s_waitcnt lgkmcnt(3)
	v_add_f32_e32 v0, v0, v144
	v_add_f32_e32 v1, v1, v145
	v_add_f32_e32 v2, v2, v146
	v_add_f32_e32 v3, v3, v147
	s_waitcnt lgkmcnt(2)
	v_add_f32_e32 v4, v4, v148
	v_add_f32_e32 v5, v5, v149
	v_add_f32_e32 v6, v6, v150
	v_add_f32_e32 v7, v7, v151
	s_waitcnt lgkmcnt(1)
	v_add_f32_e32 v8, v8, v152
	v_add_f32_e32 v9, v9, v153
	v_add_f32_e32 v10, v10, v154
	v_add_f32_e32 v11, v11, v155
	s_waitcnt lgkmcnt(0)
	v_add_f32_e32 v12, v12, v156
	v_add_f32_e32 v13, v13, v157
	v_add_f32_e32 v14, v14, v158
	v_add_f32_e32 v15, v15, v159
	v_add_f32_e32 v238, v64, v65
	v_add_f32_e32 v238, v238, v66
	v_add_f32_e32 v238, v238, v67
	v_div_scale_f32 v169, s[8:9], v238, v238, 1.0
	v_rcp_f32_e32 v170, v169
	s_nop 0
	v_fma_f32 v171, -v169, v170, 1.0
	v_fmac_f32_e32 v170, v171, v170
	v_div_scale_f32 v171, vcc, 1.0, v238, 1.0
	v_mul_f32_e32 v236, v171, v170
	v_fma_f32 v237, -v169, v236, v171
	v_fmac_f32_e32 v236, v237, v170
	v_fma_f32 v169, -v169, v236, v171
	v_div_fmas_f32 v169, v169, v170, v236
	v_div_fixup_f32 v238, v169, v238, 1.0
	v_lshl_or_b32 v235, v230, 6, v231
	v_mul_u32_u24_e32 v235, 0x110, v235
	v_lshlrev_b32_e32 v236, 1, v186
	v_add3_u32 v235, s69, v235, v236
	s_waitcnt vmcnt(8)
	ds_read_b64 v[160:161], v235 offset:128
	ds_read_b64 v[162:163], v235 offset:144
	ds_read_b64 v[164:165], v235 offset:160
	ds_read_b64 v[166:167], v235 offset:176
	v_and_b32_e32 v168, 0xffff0000, v88
	v_lshlrev_b32_e32 v169, 16, v89
	v_and_b32_e32 v170, 0xffff0000, v89
	v_lshlrev_b32_e32 v171, 16, v90
	v_and_b32_e32 v172, 0xffff0000, v90
	v_lshlrev_b32_e32 v173, 16, v91
	v_mul_f32_e32 v178, v83, v168
	v_fmac_f32_e32 v178, v82, v169
	v_fmac_f32_e32 v178, v80, v170
	v_add_f32_e32 v178, v70, v178
	v_mul_f32_e32 v179, v83, v169
	v_fmac_f32_e32 v179, v82, v170
	v_fmac_f32_e32 v179, v80, v171
	v_add_f32_e32 v179, v70, v179
	v_mul_f32_e32 v180, v83, v170
	v_fmac_f32_e32 v180, v82, v171
	v_fmac_f32_e32 v180, v80, v172
	v_add_f32_e32 v180, v70, v180
	v_mul_f32_e32 v181, v83, v171
	v_fmac_f32_e32 v181, v82, v172
	v_fmac_f32_e32 v181, v80, v173
	v_add_f32_e32 v181, v70, v181
	s_waitcnt lgkmcnt(0)
; DI float bflo(unsigned v) { return __uint_as_float(v << 16); }
; DI float bfhi(unsigned v) { return __uint_as_float(v & 0xffff0000u); }
; DI float siluf(float x) { return x * __builtin_amdgcn_rcpf(1.f + __expf(-x)); }
; DI void hyena_item(const P& p, int l, int c, char* smem) {
;     ...
;       for (int rq = 0; rq < 4; ++rq) {
;         const int bq = 32 * I + 8 * rq + 4 * g;
;         const int t4 = 128 * a + bq;
;         float px[4];
;         sconv4(rowx, t4, x0, x1, x2, xb, px);
;         const uint2 zv = *(const uint2*)(U + (bt * 64 + a) * 136 + bq);
;         const uint2 gv = *(const uint2*)(rowg + t4);
;         const float z1[4] = {bflo(zv.x), bfhi(zv.x), bflo(zv.y), bfhi(zv.y)};
;         const float gt[4] = {bflo(gv.x), bfhi(gv.x), bflo(gv.y), bfhi(gv.y)};
;         float yy[4];
; #pragma unroll
;         for (int j = 0; j < 4; ++j) yy[j] = px[j] * (acc[I][4 * rq + j] * invn1 + z1[j] * d1) * siluf(gt[j]);
;         uint2 ov; ov.x = pack2(yy[0], yy[1]); ov.y = pack2(yy[2], yy[3]);
;         *(uint2*)(dst + t4) = ov;
	v_lshlrev_b32_e32 v174, 16, v160
	v_and_b32_e32 v175, 0xffff0000, v160
	v_lshlrev_b32_e32 v176, 16, v161
	v_and_b32_e32 v177, 0xffff0000, v161
	v_mul_f32_e32 v174, v68, v174
	v_mul_f32_e32 v175, v68, v175
	v_mul_f32_e32 v176, v68, v176
	v_mul_f32_e32 v177, v68, v177
	v_fmac_f32_e32 v174, v238, v16
	v_fmac_f32_e32 v175, v238, v17
	v_fmac_f32_e32 v176, v238, v18
	v_fmac_f32_e32 v177, v238, v19
	v_mul_f32_e32 v174, v178, v174
	v_mul_f32_e32 v175, v179, v175
	v_mul_f32_e32 v176, v180, v176
	v_mul_f32_e32 v177, v181, v177
	v_lshlrev_b32_e32 v168, 16, v92
	v_and_b32_e32 v169, 0xffff0000, v92
	v_lshlrev_b32_e32 v170, 16, v93
	v_and_b32_e32 v171, 0xffff0000, v93
	v_mul_f32_e32 v178, 0xbfb8aa3b, v168
	v_mul_f32_e32 v179, 0xbfb8aa3b, v169
	v_mul_f32_e32 v180, 0xbfb8aa3b, v170
	v_mul_f32_e32 v181, 0xbfb8aa3b, v171
	v_exp_f32_e32 v178, v178
	v_exp_f32_e32 v179, v179
	v_exp_f32_e32 v180, v180
	v_exp_f32_e32 v181, v181
	v_add_f32_e32 v178, 1.0, v178
	v_add_f32_e32 v179, 1.0, v179
	v_add_f32_e32 v180, 1.0, v180
	v_add_f32_e32 v181, 1.0, v181
	v_rcp_f32_e32 v178, v178
	v_rcp_f32_e32 v179, v179
	v_rcp_f32_e32 v180, v180
	v_rcp_f32_e32 v181, v181
	v_mul_f32_e32 v178, v178, v168
	v_mul_f32_e32 v179, v179, v169
	v_mul_f32_e32 v180, v180, v170
	v_mul_f32_e32 v181, v181, v171
	v_mul_f32_e32 v174, v174, v178
	v_mul_f32_e32 v175, v175, v179
	v_mul_f32_e32 v176, v176, v180
	v_mul_f32_e32 v177, v177, v181
	v_cvt_pk_bf16_f32 v182, v174, v175
	v_cvt_pk_bf16_f32 v183, v176, v177
	global_store_dwordx2 v234, v[182:183], s[6:7] offset:128
	v_and_b32_e32 v168, 0xffff0000, v94
	v_lshlrev_b32_e32 v169, 16, v95
	v_and_b32_e32 v170, 0xffff0000, v95
	v_lshlrev_b32_e32 v171, 16, v96
	v_and_b32_e32 v172, 0xffff0000, v96
	v_lshlrev_b32_e32 v173, 16, v97
	v_mul_f32_e32 v178, v83, v168
	v_fmac_f32_e32 v178, v82, v169
	v_fmac_f32_e32 v178, v80, v170
	v_add_f32_e32 v178, v70, v178
	v_mul_f32_e32 v179, v83, v169
	v_fmac_f32_e32 v179, v82, v170
	v_fmac_f32_e32 v179, v80, v171
	v_add_f32_e32 v179, v70, v179
	v_mul_f32_e32 v180, v83, v170
	v_fmac_f32_e32 v180, v82, v171
	v_fmac_f32_e32 v180, v80, v172
	v_add_f32_e32 v180, v70, v180
	v_mul_f32_e32 v181, v83, v171
	v_fmac_f32_e32 v181, v82, v172
	v_fmac_f32_e32 v181, v80, v173
	v_add_f32_e32 v181, v70, v181
	v_lshlrev_b32_e32 v174, 16, v162
	v_and_b32_e32 v175, 0xffff0000, v162
	v_lshlrev_b32_e32 v176, 16, v163
	v_and_b32_e32 v177, 0xffff0000, v163
	v_mul_f32_e32 v174, v68, v174
	v_mul_f32_e32 v175, v68, v175
	v_mul_f32_e32 v176, v68, v176
	v_mul_f32_e32 v177, v68, v177
	v_fmac_f32_e32 v174, v238, v20
	v_fmac_f32_e32 v175, v238, v21
	v_fmac_f32_e32 v176, v238, v22
	v_fmac_f32_e32 v177, v238, v23
	v_mul_f32_e32 v174, v178, v174
	v_mul_f32_e32 v175, v179, v175
	v_mul_f32_e32 v176, v180, v176
	v_mul_f32_e32 v177, v181, v177
	v_lshlrev_b32_e32 v168, 16, v98
	v_and_b32_e32 v169, 0xffff0000, v98
	v_lshlrev_b32_e32 v170, 16, v99
	v_and_b32_e32 v171, 0xffff0000, v99
	v_mul_f32_e32 v178, 0xbfb8aa3b, v168
	v_mul_f32_e32 v179, 0xbfb8aa3b, v169
	v_mul_f32_e32 v180, 0xbfb8aa3b, v170
	v_mul_f32_e32 v181, 0xbfb8aa3b, v171
	v_exp_f32_e32 v178, v178
	v_exp_f32_e32 v179, v179
	v_exp_f32_e32 v180, v180
	v_exp_f32_e32 v181, v181
	v_add_f32_e32 v178, 1.0, v178
	v_add_f32_e32 v179, 1.0, v179
	v_add_f32_e32 v180, 1.0, v180
	v_add_f32_e32 v181, 1.0, v181
	v_rcp_f32_e32 v178, v178
	v_rcp_f32_e32 v179, v179
	v_rcp_f32_e32 v180, v180
	v_rcp_f32_e32 v181, v181
	v_mul_f32_e32 v178, v178, v168
	v_mul_f32_e32 v179, v179, v169
	v_mul_f32_e32 v180, v180, v170
	v_mul_f32_e32 v181, v181, v171
	v_mul_f32_e32 v174, v174, v178
	v_mul_f32_e32 v175, v175, v179
	v_mul_f32_e32 v176, v176, v180
	v_mul_f32_e32 v177, v177, v181
	v_cvt_pk_bf16_f32 v182, v174, v175
	v_cvt_pk_bf16_f32 v183, v176, v177
	global_store_dwordx2 v234, v[182:183], s[6:7] offset:144
	v_and_b32_e32 v168, 0xffff0000, v100
	v_lshlrev_b32_e32 v169, 16, v101
	v_and_b32_e32 v170, 0xffff0000, v101
	v_lshlrev_b32_e32 v171, 16, v102
	v_and_b32_e32 v172, 0xffff0000, v102
	v_lshlrev_b32_e32 v173, 16, v103
	v_mul_f32_e32 v178, v83, v168
	v_fmac_f32_e32 v178, v82, v169
	v_fmac_f32_e32 v178, v80, v170
	v_add_f32_e32 v178, v70, v178
	v_mul_f32_e32 v179, v83, v169
	v_fmac_f32_e32 v179, v82, v170
	v_fmac_f32_e32 v179, v80, v171
	v_add_f32_e32 v179, v70, v179
	v_mul_f32_e32 v180, v83, v170
	v_fmac_f32_e32 v180, v82, v171
	v_fmac_f32_e32 v180, v80, v172
	v_add_f32_e32 v180, v70, v180
	v_mul_f32_e32 v181, v83, v171
	v_fmac_f32_e32 v181, v82, v172
	v_fmac_f32_e32 v181, v80, v173
	v_add_f32_e32 v181, v70, v181
	v_lshlrev_b32_e32 v174, 16, v164
	v_and_b32_e32 v175, 0xffff0000, v164
	v_lshlrev_b32_e32 v176, 16, v165
	v_and_b32_e32 v177, 0xffff0000, v165
	v_mul_f32_e32 v174, v68, v174
	v_mul_f32_e32 v175, v68, v175
	v_mul_f32_e32 v176, v68, v176
	v_mul_f32_e32 v177, v68, v177
	v_fmac_f32_e32 v174, v238, v24
	v_fmac_f32_e32 v175, v238, v25
	v_fmac_f32_e32 v176, v238, v26
	v_fmac_f32_e32 v177, v238, v27
	v_mul_f32_e32 v174, v178, v174
	v_mul_f32_e32 v175, v179, v175
	v_mul_f32_e32 v176, v180, v176
	v_mul_f32_e32 v177, v181, v177
	v_lshlrev_b32_e32 v168, 16, v104
	v_and_b32_e32 v169, 0xffff0000, v104
	v_lshlrev_b32_e32 v170, 16, v105
	v_and_b32_e32 v171, 0xffff0000, v105
	v_mul_f32_e32 v178, 0xbfb8aa3b, v168
	v_mul_f32_e32 v179, 0xbfb8aa3b, v169
	v_mul_f32_e32 v180, 0xbfb8aa3b, v170
	v_mul_f32_e32 v181, 0xbfb8aa3b, v171
	v_exp_f32_e32 v178, v178
	v_exp_f32_e32 v179, v179
	v_exp_f32_e32 v180, v180
	v_exp_f32_e32 v181, v181
	v_add_f32_e32 v178, 1.0, v178
	v_add_f32_e32 v179, 1.0, v179
	v_add_f32_e32 v180, 1.0, v180
	v_add_f32_e32 v181, 1.0, v181
	v_rcp_f32_e32 v178, v178
	v_rcp_f32_e32 v179, v179
	v_rcp_f32_e32 v180, v180
; DI float bflo(unsigned v) { return __uint_as_float(v << 16); }
; DI float bfhi(unsigned v) { return __uint_as_float(v & 0xffff0000u); }
; DI float siluf(float x) { return x * __builtin_amdgcn_rcpf(1.f + __expf(-x)); }
; DI void hyena_item(const P& p, int l, int c, char* smem) {
;     ...
;       for (int rq = 0; rq < 4; ++rq) {
;         const int bq = 32 * I + 8 * rq + 4 * g;
;         const int t4 = 128 * a + bq;
;         float px[4];
;         sconv4(rowx, t4, x0, x1, x2, xb, px);
;         const uint2 zv = *(const uint2*)(U + (bt * 64 + a) * 136 + bq);
;         const uint2 gv = *(const uint2*)(rowg + t4);
;         const float z1[4] = {bflo(zv.x), bfhi(zv.x), bflo(zv.y), bfhi(zv.y)};
;         const float gt[4] = {bflo(gv.x), bfhi(gv.x), bflo(gv.y), bfhi(gv.y)};
;         float yy[4];
; #pragma unroll
;         for (int j = 0; j < 4; ++j) yy[j] = px[j] * (acc[I][4 * rq + j] * invn1 + z1[j] * d1) * siluf(gt[j]);
;         uint2 ov; ov.x = pack2(yy[0], yy[1]); ov.y = pack2(yy[2], yy[3]);
;         *(uint2*)(dst + t4) = ov;
	v_rcp_f32_e32 v181, v181
	v_mul_f32_e32 v178, v178, v168
	v_mul_f32_e32 v179, v179, v169
	v_mul_f32_e32 v180, v180, v170
	v_mul_f32_e32 v181, v181, v171
	v_mul_f32_e32 v174, v174, v178
	v_mul_f32_e32 v175, v175, v179
	v_mul_f32_e32 v176, v176, v180
	v_mul_f32_e32 v177, v177, v181
	v_cvt_pk_bf16_f32 v182, v174, v175
	v_cvt_pk_bf16_f32 v183, v176, v177
	global_store_dwordx2 v234, v[182:183], s[6:7] offset:160
	v_and_b32_e32 v168, 0xffff0000, v106
	v_lshlrev_b32_e32 v169, 16, v107
	v_and_b32_e32 v170, 0xffff0000, v107
	v_lshlrev_b32_e32 v171, 16, v108
	v_and_b32_e32 v172, 0xffff0000, v108
	v_lshlrev_b32_e32 v173, 16, v109
	v_mul_f32_e32 v178, v83, v168
	v_fmac_f32_e32 v178, v82, v169
	v_fmac_f32_e32 v178, v80, v170
	v_add_f32_e32 v178, v70, v178
	v_mul_f32_e32 v179, v83, v169
	v_fmac_f32_e32 v179, v82, v170
	v_fmac_f32_e32 v179, v80, v171
	v_add_f32_e32 v179, v70, v179
	v_mul_f32_e32 v180, v83, v170
	v_fmac_f32_e32 v180, v82, v171
	v_fmac_f32_e32 v180, v80, v172
	v_add_f32_e32 v180, v70, v180
	v_mul_f32_e32 v181, v83, v171
	v_fmac_f32_e32 v181, v82, v172
	v_fmac_f32_e32 v181, v80, v173
	v_add_f32_e32 v181, v70, v181
	v_lshlrev_b32_e32 v174, 16, v166
	v_and_b32_e32 v175, 0xffff0000, v166
	v_lshlrev_b32_e32 v176, 16, v167
	v_and_b32_e32 v177, 0xffff0000, v167
	v_mul_f32_e32 v174, v68, v174
	v_mul_f32_e32 v175, v68, v175
	v_mul_f32_e32 v176, v68, v176
	v_mul_f32_e32 v177, v68, v177
	v_fmac_f32_e32 v174, v238, v28
	v_fmac_f32_e32 v175, v238, v29
	v_fmac_f32_e32 v176, v238, v30
	v_fmac_f32_e32 v177, v238, v31
	v_mul_f32_e32 v174, v178, v174
	v_mul_f32_e32 v175, v179, v175
	v_mul_f32_e32 v176, v180, v176
	v_mul_f32_e32 v177, v181, v177
	v_lshlrev_b32_e32 v168, 16, v110
	v_and_b32_e32 v169, 0xffff0000, v110
	v_lshlrev_b32_e32 v170, 16, v111
	v_and_b32_e32 v171, 0xffff0000, v111
	v_mul_f32_e32 v178, 0xbfb8aa3b, v168
	v_mul_f32_e32 v179, 0xbfb8aa3b, v169
	v_mul_f32_e32 v180, 0xbfb8aa3b, v170
	v_mul_f32_e32 v181, 0xbfb8aa3b, v171
	v_exp_f32_e32 v178, v178
	v_exp_f32_e32 v179, v179
	v_exp_f32_e32 v180, v180
	v_exp_f32_e32 v181, v181
	v_add_f32_e32 v178, 1.0, v178
	v_add_f32_e32 v179, 1.0, v179
	v_add_f32_e32 v180, 1.0, v180
	v_add_f32_e32 v181, 1.0, v181
	v_rcp_f32_e32 v178, v178
	v_rcp_f32_e32 v179, v179
	v_rcp_f32_e32 v180, v180
	v_rcp_f32_e32 v181, v181
	v_mul_f32_e32 v178, v178, v168
	v_mul_f32_e32 v179, v179, v169
	v_mul_f32_e32 v180, v180, v170
	v_mul_f32_e32 v181, v181, v171
	v_mul_f32_e32 v174, v174, v178
	v_mul_f32_e32 v175, v175, v179
	v_mul_f32_e32 v176, v176, v180
	v_mul_f32_e32 v177, v177, v181
	v_cvt_pk_bf16_f32 v182, v174, v175
	v_cvt_pk_bf16_f32 v183, v176, v177
	global_store_dwordx2 v234, v[182:183], s[6:7] offset:176
	s_waitcnt vmcnt(4)
	ds_read_b64 v[160:161], v235 offset:192
	ds_read_b64 v[162:163], v235 offset:208
	ds_read_b64 v[164:165], v235 offset:224
	ds_read_b64 v[166:167], v235 offset:240
	v_and_b32_e32 v168, 0xffff0000, v112
	v_lshlrev_b32_e32 v169, 16, v113
	v_and_b32_e32 v170, 0xffff0000, v113
	v_lshlrev_b32_e32 v171, 16, v114
	v_and_b32_e32 v172, 0xffff0000, v114
	v_lshlrev_b32_e32 v173, 16, v115
	v_mul_f32_e32 v178, v83, v168
	v_fmac_f32_e32 v178, v82, v169
	v_fmac_f32_e32 v178, v80, v170
	v_add_f32_e32 v178, v70, v178
	v_mul_f32_e32 v179, v83, v169
	v_fmac_f32_e32 v179, v82, v170
	v_fmac_f32_e32 v179, v80, v171
	v_add_f32_e32 v179, v70, v179
	v_mul_f32_e32 v180, v83, v170
	v_fmac_f32_e32 v180, v82, v171
	v_fmac_f32_e32 v180, v80, v172
	v_add_f32_e32 v180, v70, v180
	v_mul_f32_e32 v181, v83, v171
	v_fmac_f32_e32 v181, v82, v172
	v_fmac_f32_e32 v181, v80, v173
	v_add_f32_e32 v181, v70, v181
	s_waitcnt lgkmcnt(0)
	v_lshlrev_b32_e32 v174, 16, v160
	v_and_b32_e32 v175, 0xffff0000, v160
	v_lshlrev_b32_e32 v176, 16, v161
	v_and_b32_e32 v177, 0xffff0000, v161
	v_mul_f32_e32 v174, v68, v174
	v_mul_f32_e32 v175, v68, v175
	v_mul_f32_e32 v176, v68, v176
	v_mul_f32_e32 v177, v68, v177
	v_fmac_f32_e32 v174, v238, v0
	v_fmac_f32_e32 v175, v238, v1
	v_fmac_f32_e32 v176, v238, v2
	v_fmac_f32_e32 v177, v238, v3
	v_mul_f32_e32 v174, v178, v174
	v_mul_f32_e32 v175, v179, v175
	v_mul_f32_e32 v176, v180, v176
	v_mul_f32_e32 v177, v181, v177
	v_lshlrev_b32_e32 v168, 16, v116
	v_and_b32_e32 v169, 0xffff0000, v116
	v_lshlrev_b32_e32 v170, 16, v117
	v_and_b32_e32 v171, 0xffff0000, v117
	v_mul_f32_e32 v178, 0xbfb8aa3b, v168
	v_mul_f32_e32 v179, 0xbfb8aa3b, v169
	v_mul_f32_e32 v180, 0xbfb8aa3b, v170
	v_mul_f32_e32 v181, 0xbfb8aa3b, v171
	v_exp_f32_e32 v178, v178
	v_exp_f32_e32 v179, v179
	v_exp_f32_e32 v180, v180
	v_exp_f32_e32 v181, v181
	v_add_f32_e32 v178, 1.0, v178
	v_add_f32_e32 v179, 1.0, v179
	v_add_f32_e32 v180, 1.0, v180
	v_add_f32_e32 v181, 1.0, v181
	v_rcp_f32_e32 v178, v178
	v_rcp_f32_e32 v179, v179
	v_rcp_f32_e32 v180, v180
	v_rcp_f32_e32 v181, v181
	v_mul_f32_e32 v178, v178, v168
	v_mul_f32_e32 v179, v179, v169
	v_mul_f32_e32 v180, v180, v170
	v_mul_f32_e32 v181, v181, v171
	v_mul_f32_e32 v174, v174, v178
	v_mul_f32_e32 v175, v175, v179
	v_mul_f32_e32 v176, v176, v180
	v_mul_f32_e32 v177, v177, v181
	v_cvt_pk_bf16_f32 v182, v174, v175
	v_cvt_pk_bf16_f32 v183, v176, v177
	global_store_dwordx2 v234, v[182:183], s[6:7] offset:192
	v_and_b32_e32 v168, 0xffff0000, v118
	v_lshlrev_b32_e32 v169, 16, v119
	v_and_b32_e32 v170, 0xffff0000, v119
	v_lshlrev_b32_e32 v171, 16, v120
	v_and_b32_e32 v172, 0xffff0000, v120
	v_lshlrev_b32_e32 v173, 16, v121
	v_mul_f32_e32 v178, v83, v168
	v_fmac_f32_e32 v178, v82, v169
	v_fmac_f32_e32 v178, v80, v170
	v_add_f32_e32 v178, v70, v178
	v_mul_f32_e32 v179, v83, v169
	v_fmac_f32_e32 v179, v82, v170
	v_fmac_f32_e32 v179, v80, v171
	v_add_f32_e32 v179, v70, v179
	v_mul_f32_e32 v180, v83, v170
; DI float bf2f(unsigned v) { return __uint_as_float(v << 16); }
; DI float bflo(unsigned v) { return __uint_as_float(v << 16); }
; DI float bfhi(unsigned v) { return __uint_as_float(v & 0xffff0000u); }
; DI float siluf(float x) { return x * __builtin_amdgcn_rcpf(1.f + __expf(-x)); }
; DI void sconv4(const u16* row, int t4, float w0, float w1, float w2, float bias, float (&o)[4]) {
;     ...
;   const float xp = (t4 + 4 < SEQ) ? bf2f(row[t4 + 4]) : 0.f;
; DI void hyena_item(const P& p, int l, int c, char* smem) {
;     ...
;       for (int rq = 0; rq < 4; ++rq) {
;         const int bq = 32 * I + 8 * rq + 4 * g;
;         const int t4 = 128 * a + bq;
;         float px[4];
;         sconv4(rowx, t4, x0, x1, x2, xb, px);
;         const uint2 zv = *(const uint2*)(U + (bt * 64 + a) * 136 + bq);
;         const uint2 gv = *(const uint2*)(rowg + t4);
;         const float z1[4] = {bflo(zv.x), bfhi(zv.x), bflo(zv.y), bfhi(zv.y)};
;         const float gt[4] = {bflo(gv.x), bfhi(gv.x), bflo(gv.y), bfhi(gv.y)};
;         float yy[4];
; #pragma unroll
;         for (int j = 0; j < 4; ++j) yy[j] = px[j] * (acc[I][4 * rq + j] * invn1 + z1[j] * d1) * siluf(gt[j]);
;         uint2 ov; ov.x = pack2(yy[0], yy[1]); ov.y = pack2(yy[2], yy[3]);
;         *(uint2*)(dst + t4) = ov;
	v_fmac_f32_e32 v180, v82, v171
	v_fmac_f32_e32 v180, v80, v172
	v_add_f32_e32 v180, v70, v180
	v_mul_f32_e32 v181, v83, v171
	v_fmac_f32_e32 v181, v82, v172
	v_fmac_f32_e32 v181, v80, v173
	v_add_f32_e32 v181, v70, v181
	v_lshlrev_b32_e32 v174, 16, v162
	v_and_b32_e32 v175, 0xffff0000, v162
	v_lshlrev_b32_e32 v176, 16, v163
	v_and_b32_e32 v177, 0xffff0000, v163
	v_mul_f32_e32 v174, v68, v174
	v_mul_f32_e32 v175, v68, v175
	v_mul_f32_e32 v176, v68, v176
	v_mul_f32_e32 v177, v68, v177
	v_fmac_f32_e32 v174, v238, v4
	v_fmac_f32_e32 v175, v238, v5
	v_fmac_f32_e32 v176, v238, v6
	v_fmac_f32_e32 v177, v238, v7
	v_mul_f32_e32 v174, v178, v174
	v_mul_f32_e32 v175, v179, v175
	v_mul_f32_e32 v176, v180, v176
	v_mul_f32_e32 v177, v181, v177
	v_lshlrev_b32_e32 v168, 16, v122
	v_and_b32_e32 v169, 0xffff0000, v122
	v_lshlrev_b32_e32 v170, 16, v123
	v_and_b32_e32 v171, 0xffff0000, v123
	v_mul_f32_e32 v178, 0xbfb8aa3b, v168
	v_mul_f32_e32 v179, 0xbfb8aa3b, v169
	v_mul_f32_e32 v180, 0xbfb8aa3b, v170
	v_mul_f32_e32 v181, 0xbfb8aa3b, v171
	v_exp_f32_e32 v178, v178
	v_exp_f32_e32 v179, v179
	v_exp_f32_e32 v180, v180
	v_exp_f32_e32 v181, v181
	v_add_f32_e32 v178, 1.0, v178
	v_add_f32_e32 v179, 1.0, v179
	v_add_f32_e32 v180, 1.0, v180
	v_add_f32_e32 v181, 1.0, v181
	v_rcp_f32_e32 v178, v178
	v_rcp_f32_e32 v179, v179
	v_rcp_f32_e32 v180, v180
	v_rcp_f32_e32 v181, v181
	v_mul_f32_e32 v178, v178, v168
	v_mul_f32_e32 v179, v179, v169
	v_mul_f32_e32 v180, v180, v170
	v_mul_f32_e32 v181, v181, v171
	v_mul_f32_e32 v174, v174, v178
	v_mul_f32_e32 v175, v175, v179
	v_mul_f32_e32 v176, v176, v180
	v_mul_f32_e32 v177, v177, v181
	v_cvt_pk_bf16_f32 v182, v174, v175
	v_cvt_pk_bf16_f32 v183, v176, v177
	global_store_dwordx2 v234, v[182:183], s[6:7] offset:208
	v_and_b32_e32 v168, 0xffff0000, v124
	v_lshlrev_b32_e32 v169, 16, v125
	v_and_b32_e32 v170, 0xffff0000, v125
	v_lshlrev_b32_e32 v171, 16, v126
	v_and_b32_e32 v172, 0xffff0000, v126
	v_lshlrev_b32_e32 v173, 16, v127
	v_mul_f32_e32 v178, v83, v168
	v_fmac_f32_e32 v178, v82, v169
	v_fmac_f32_e32 v178, v80, v170
	v_add_f32_e32 v178, v70, v178
	v_mul_f32_e32 v179, v83, v169
	v_fmac_f32_e32 v179, v82, v170
	v_fmac_f32_e32 v179, v80, v171
	v_add_f32_e32 v179, v70, v179
	v_mul_f32_e32 v180, v83, v170
	v_fmac_f32_e32 v180, v82, v171
	v_fmac_f32_e32 v180, v80, v172
	v_add_f32_e32 v180, v70, v180
	v_mul_f32_e32 v181, v83, v171
	v_fmac_f32_e32 v181, v82, v172
	v_fmac_f32_e32 v181, v80, v173
	v_add_f32_e32 v181, v70, v181
	v_lshlrev_b32_e32 v174, 16, v164
	v_and_b32_e32 v175, 0xffff0000, v164
	v_lshlrev_b32_e32 v176, 16, v165
	v_and_b32_e32 v177, 0xffff0000, v165
	v_mul_f32_e32 v174, v68, v174
	v_mul_f32_e32 v175, v68, v175
	v_mul_f32_e32 v176, v68, v176
	v_mul_f32_e32 v177, v68, v177
	v_fmac_f32_e32 v174, v238, v8
	v_fmac_f32_e32 v175, v238, v9
	v_fmac_f32_e32 v176, v238, v10
	v_fmac_f32_e32 v177, v238, v11
	v_mul_f32_e32 v174, v178, v174
	v_mul_f32_e32 v175, v179, v175
	v_mul_f32_e32 v176, v180, v176
	v_mul_f32_e32 v177, v181, v177
	v_lshlrev_b32_e32 v168, 16, v128
	v_and_b32_e32 v169, 0xffff0000, v128
	v_lshlrev_b32_e32 v170, 16, v129
	v_and_b32_e32 v171, 0xffff0000, v129
	v_mul_f32_e32 v178, 0xbfb8aa3b, v168
	v_mul_f32_e32 v179, 0xbfb8aa3b, v169
	v_mul_f32_e32 v180, 0xbfb8aa3b, v170
	v_mul_f32_e32 v181, 0xbfb8aa3b, v171
	v_exp_f32_e32 v178, v178
	v_exp_f32_e32 v179, v179
	v_exp_f32_e32 v180, v180
	v_exp_f32_e32 v181, v181
	v_add_f32_e32 v178, 1.0, v178
	v_add_f32_e32 v179, 1.0, v179
	v_add_f32_e32 v180, 1.0, v180
	v_add_f32_e32 v181, 1.0, v181
	v_rcp_f32_e32 v178, v178
	v_rcp_f32_e32 v179, v179
	v_rcp_f32_e32 v180, v180
	v_rcp_f32_e32 v181, v181
	v_mul_f32_e32 v178, v178, v168
	v_mul_f32_e32 v179, v179, v169
	v_mul_f32_e32 v180, v180, v170
	v_mul_f32_e32 v181, v181, v171
	v_mul_f32_e32 v174, v174, v178
	v_mul_f32_e32 v175, v175, v179
	v_mul_f32_e32 v176, v176, v180
	v_mul_f32_e32 v177, v177, v181
	v_cvt_pk_bf16_f32 v182, v174, v175
	v_cvt_pk_bf16_f32 v183, v176, v177
	global_store_dwordx2 v234, v[182:183], s[6:7] offset:224
	v_cmp_ne_u32_e32 vcc, 0x1f84, v233
	s_nop 1
	v_and_b32_e32 v168, 0xffff0000, v130
	v_lshlrev_b32_e32 v169, 16, v131
	v_and_b32_e32 v170, 0xffff0000, v131
	v_lshlrev_b32_e32 v171, 16, v132
	v_and_b32_e32 v172, 0xffff0000, v132
	v_lshlrev_b32_e32 v173, 16, v133
	v_cndmask_b32_e32 v173, 0, v173, vcc
	v_mul_f32_e32 v178, v83, v168
	v_fmac_f32_e32 v178, v82, v169
	v_fmac_f32_e32 v178, v80, v170
	v_add_f32_e32 v178, v70, v178
	v_mul_f32_e32 v179, v83, v169
	v_fmac_f32_e32 v179, v82, v170
	v_fmac_f32_e32 v179, v80, v171
	v_add_f32_e32 v179, v70, v179
	v_mul_f32_e32 v180, v83, v170
	v_fmac_f32_e32 v180, v82, v171
	v_fmac_f32_e32 v180, v80, v172
	v_add_f32_e32 v180, v70, v180
	v_mul_f32_e32 v181, v83, v171
	v_fmac_f32_e32 v181, v82, v172
	v_fmac_f32_e32 v181, v80, v173
	v_add_f32_e32 v181, v70, v181
	v_lshlrev_b32_e32 v174, 16, v166
	v_and_b32_e32 v175, 0xffff0000, v166
	v_lshlrev_b32_e32 v176, 16, v167
	v_and_b32_e32 v177, 0xffff0000, v167
	v_mul_f32_e32 v174, v68, v174
	v_mul_f32_e32 v175, v68, v175
	v_mul_f32_e32 v176, v68, v176
	v_mul_f32_e32 v177, v68, v177
	v_fmac_f32_e32 v174, v238, v12
	v_fmac_f32_e32 v175, v238, v13
	v_fmac_f32_e32 v176, v238, v14
	v_fmac_f32_e32 v177, v238, v15
	v_mul_f32_e32 v174, v178, v174
	v_mul_f32_e32 v175, v179, v175
	v_mul_f32_e32 v176, v180, v176
	v_mul_f32_e32 v177, v181, v177
	v_lshlrev_b32_e32 v168, 16, v134
	v_and_b32_e32 v169, 0xffff0000, v134
	v_lshlrev_b32_e32 v170, 16, v135
	v_and_b32_e32 v171, 0xffff0000, v135
	v_mul_f32_e32 v178, 0xbfb8aa3b, v168
	v_mul_f32_e32 v179, 0xbfb8aa3b, v169
	v_mul_f32_e32 v180, 0xbfb8aa3b, v170
	v_mul_f32_e32 v181, 0xbfb8aa3b, v171
	v_exp_f32_e32 v178, v178
	v_exp_f32_e32 v179, v179
	v_exp_f32_e32 v180, v180
	v_exp_f32_e32 v181, v181
	v_add_f32_e32 v178, 1.0, v178
	v_add_f32_e32 v179, 1.0, v179
	v_add_f32_e32 v180, 1.0, v180
	v_add_f32_e32 v181, 1.0, v181
	v_rcp_f32_e32 v178, v178
	v_rcp_f32_e32 v179, v179
	v_rcp_f32_e32 v180, v180
	v_rcp_f32_e32 v181, v181
	v_mul_f32_e32 v178, v178, v168
	v_mul_f32_e32 v179, v179, v169
	v_mul_f32_e32 v180, v180, v170
	v_mul_f32_e32 v181, v181, v171
	v_mul_f32_e32 v174, v174, v178
	v_mul_f32_e32 v175, v175, v179
	v_mul_f32_e32 v176, v176, v180
	v_mul_f32_e32 v177, v177, v181
	v_cvt_pk_bf16_f32 v182, v174, v175
	v_cvt_pk_bf16_f32 v183, v176, v177
	global_store_dwordx2 v234, v[182:183], s[6:7] offset:240
